# counted waits: post-projection next-row touch issued right after the rope-table loads (earlier in the row), later waits raised by the 5 touch loads (on top of v42)
# speedup vs baseline: 1.0009x; 1.0009x over previous
.LBB0_334:
	s_or_b64 exec, exec, s[0:1]
	v_lshlrev_b32_e32 v130, 4, v130
	v_ashrrev_i32_e32 v131, 31, v130
	v_lshl_add_u64 v[138:139], v[130:131], 2, v[150:151]
	s_mov_b64 s[0:1], 0x2000
	v_lshl_add_u64 v[140:141], v[138:139], 0, s[0:1]
	s_movk_i32 s0, 0x2000
	global_load_dwordx4 v[134:137], v[138:139], off
	global_load_dwordx4 v[130:133], v[138:139], off offset:16
	v_add_co_u32_e32 v138, vcc, s0, v138
	s_waitcnt vmcnt(5)
	v_lshlrev_b32_e32 v164, 16, v146
	v_addc_co_u32_e32 v139, vcc, 0, v139, vcc
	global_load_dwordx4 v[142:145], v[138:139], off
	s_nop 0
	global_load_dwordx4 v[138:141], v[140:141], off offset:16
	s_mov_b64 s[0:1], 0xc302000
	v_lshl_add_u64 v[192:193], s[16:17], 0, v[0:1]
	s_nop 0
	v_lshl_add_u64 v[192:193], v[192:193], 0, s[0:1]
	global_load_dwordx4 v[182:185], v[192:193], off offset:-3584
	global_load_dwordx4 v[182:185], v[192:193], off offset:-512
	global_load_dwordx4 v[182:185], v[192:193], off offset:512
	global_load_dwordx4 v[182:185], v[192:193], off offset:2048
	global_load_dwordx4 v[182:185], v[192:193], off offset:3072
	v_and_b32_e32 v165, 0xffff0000, v146
	v_lshlrev_b32_e32 v160, 16, v147
	v_and_b32_e32 v161, 0xffff0000, v147
	v_pk_mul_f32 v[146:147], v[164:165], v[164:165]
	v_pk_mul_f32 v[162:163], v[160:161], v[160:161]
	v_add_f32_e32 v146, v146, v147
	v_lshlrev_b32_e32 v158, 16, v148
	v_and_b32_e32 v159, 0xffff0000, v148
	v_add_f32_e32 v146, v162, v146
	v_lshlrev_b32_e32 v154, 16, v149
	v_and_b32_e32 v155, 0xffff0000, v149
	v_pk_mul_f32 v[148:149], v[158:159], v[158:159]
	v_add_f32_e32 v146, v163, v146
	v_add_f32_e32 v146, v148, v146
	v_pk_mul_f32 v[156:157], v[154:155], v[154:155]
	v_add_f32_e32 v146, v149, v146
	v_add_f32_e32 v146, v156, v146
	v_add_f32_e32 v146, v157, v146
	ds_bpermute_b32 v147, v176, v146
	s_waitcnt lgkmcnt(0)
	v_add_f32_e32 v146, v146, v147
	ds_bpermute_b32 v147, v177, v146
	s_waitcnt lgkmcnt(0)
	v_add_f32_e32 v146, v146, v147
	ds_bpermute_b32 v147, v178, v146
	s_waitcnt lgkmcnt(0)
	v_add_f32_e32 v146, v146, v147
	v_fmamk_f32 v146, v146, 0x3c800000, v199
	v_cmp_gt_f32_e32 vcc, s21, v146
	v_mul_f32_e32 v147, 0x4f800000, v146
	s_nop 0
	v_cndmask_b32_e32 v146, v146, v147, vcc
	v_sqrt_f32_e32 v147, v146
	s_nop 0
	v_add_u32_e32 v148, -1, v147
	v_fma_f32 v149, -v148, v147, v146
	v_cmp_ge_f32_e64 s[50:51], 0, v149
	v_add_u32_e32 v149, 1, v147
	s_nop 0
	v_cndmask_b32_e64 v148, v147, v148, s[50:51]
	v_fma_f32 v147, -v149, v147, v146
	v_cmp_lt_f32_e64 s[50:51], 0, v147
	s_nop 1
	v_cndmask_b32_e64 v147, v148, v149, s[50:51]
	v_mul_f32_e32 v148, 0x37800000, v147
	v_cndmask_b32_e32 v147, v147, v148, vcc
	v_cmp_class_f32_e32 vcc, v146, v200
	s_nop 1
	v_cndmask_b32_e32 v146, v147, v146, vcc
	v_div_scale_f32 v147, s[0:1], v146, v146, 1.0
	v_rcp_f32_e32 v148, v147
	s_nop 0
	v_fma_f32 v149, -v147, v148, 1.0
	v_fmac_f32_e32 v148, v149, v148
	v_div_scale_f32 v149, vcc, 1.0, v146, 1.0
	v_mul_f32_e32 v156, v149, v148
	v_fma_f32 v157, -v147, v156, v149
	v_fmac_f32_e32 v156, v157, v148
	v_fma_f32 v147, -v147, v156, v149
	v_div_fmas_f32 v147, v147, v148, v156
	v_div_fixup_f32 v146, v147, v146, 1.0
	v_pk_mul_f32 v[148:149], v[146:147], v[164:165] op_sel_hi:[0,1]
	v_pk_mul_f32 v[148:149], v[14:15], v[148:149]
	v_pk_mul_f32 v[156:157], v[146:147], v[160:161] op_sel_hi:[0,1]
	v_pk_mul_f32 v[158:159], v[146:147], v[158:159] op_sel_hi:[0,1]
	v_pk_mul_f32 v[146:147], v[146:147], v[154:155] op_sel_hi:[0,1]
	ds_bpermute_b32 v154, v177, v148
	ds_bpermute_b32 v155, v177, v149
	v_pk_mul_f32 v[156:157], v[16:17], v[156:157]
	v_pk_mul_f32 v[158:159], v[10:11], v[158:159]
	v_pk_mul_f32 v[146:147], v[12:13], v[146:147]
	s_waitcnt vmcnt(6) lgkmcnt(0)
	v_pk_mul_f32 v[154:155], v[142:143], v[154:155]
	s_nop 0
	v_cndmask_b32_e64 v155, v155, -v155, s[44:45]
	v_cndmask_b32_e64 v154, v154, -v154, s[44:45]
	v_pk_fma_f32 v[148:149], v[134:135], v[148:149], v[154:155]
	ds_bpermute_b32 v154, v177, v156
	ds_bpermute_b32 v155, v177, v157
	v_pk_mul_f32 v[148:149], v[148:149], s[20:21] op_sel_hi:[1,0]
	s_waitcnt lgkmcnt(0)
	v_pk_mul_f32 v[154:155], v[144:145], v[154:155]
	s_nop 0
	v_cndmask_b32_e64 v155, v155, -v155, s[44:45]
	v_cndmask_b32_e64 v154, v154, -v154, s[44:45]
	v_pk_fma_f32 v[154:155], v[136:137], v[156:157], v[154:155]
	ds_bpermute_b32 v156, v177, v158
	ds_bpermute_b32 v157, v177, v159
	v_pk_mul_f32 v[154:155], v[154:155], s[20:21] op_sel_hi:[1,0]
	s_waitcnt vmcnt(5) lgkmcnt(0)
	v_pk_mul_f32 v[156:157], v[138:139], v[156:157]
	s_nop 0
	v_cndmask_b32_e64 v157, v157, -v157, s[44:45]
	v_cndmask_b32_e64 v156, v156, -v156, s[44:45]
	v_pk_fma_f32 v[156:157], v[130:131], v[158:159], v[156:157]
	ds_bpermute_b32 v158, v177, v146
	ds_bpermute_b32 v159, v177, v147
	v_pk_mul_f32 v[156:157], v[156:157], s[20:21] op_sel_hi:[1,0]
	s_waitcnt lgkmcnt(0)
	v_pk_mul_f32 v[158:159], v[140:141], v[158:159]
	s_nop 0
	v_cndmask_b32_e64 v159, v159, -v159, s[44:45]
	v_cndmask_b32_e64 v158, v158, -v158, s[44:45]
	v_pk_fma_f32 v[146:147], v[132:133], v[146:147], v[158:159]
	s_nop 0
	v_pk_mul_f32 v[158:159], v[146:147], s[20:21] op_sel_hi:[1,0]
	v_cvt_pk_bf16_f32 v146, v148, v149
	v_cvt_pk_bf16_f32 v147, v154, v155
	v_cvt_pk_bf16_f32 v148, v156, v157
	v_cvt_pk_bf16_f32 v149, v158, v159
	v_lshl_add_u64 v[154:155], s[10:11], 0, v[0:1]
	v_lshlrev_b32_e32 v156, 16, v126
	v_and_b32_e32 v157, 0xffff0000, v126
	global_store_dwordx4 v[154:155], v[146:149], off
	v_lshlrev_b32_e32 v154, 16, v127
	v_and_b32_e32 v155, 0xffff0000, v127
	v_pk_mul_f32 v[164:165], v[156:157], v[156:157]
	v_pk_mul_f32 v[158:159], v[154:155], v[154:155]
	v_add_f32_e32 v164, v164, v165
	v_lshlrev_b32_e32 v148, 16, v128
	v_and_b32_e32 v149, 0xffff0000, v128
	v_add_f32_e32 v158, v158, v164
	v_pk_mul_f32 v[160:161], v[148:149], v[148:149]
	v_add_f32_e32 v158, v159, v158
	v_lshlrev_b32_e32 v146, 16, v129
	v_and_b32_e32 v147, 0xffff0000, v129
	v_add_f32_e32 v158, v160, v158
	v_pk_mul_f32 v[162:163], v[146:147], v[146:147]
	v_add_f32_e32 v158, v161, v158
	v_add_f32_e32 v158, v162, v158
	v_add_f32_e32 v158, v163, v158
	ds_bpermute_b32 v159, v176, v158
	s_waitcnt lgkmcnt(0)
	v_add_f32_e32 v158, v158, v159
	ds_bpermute_b32 v159, v177, v158
	s_waitcnt lgkmcnt(0)
	v_add_f32_e32 v158, v158, v159
	ds_bpermute_b32 v159, v178, v158
	s_waitcnt lgkmcnt(0)
	v_add_f32_e32 v158, v158, v159
	v_fmamk_f32 v158, v158, 0x3c800000, v199
	v_cmp_gt_f32_e32 vcc, s21, v158
	v_mul_f32_e32 v159, 0x4f800000, v158
	s_nop 0
	v_cndmask_b32_e32 v158, v158, v159, vcc
	v_sqrt_f32_e32 v159, v158
	s_nop 0
	v_add_u32_e32 v160, -1, v159
	v_fma_f32 v161, -v160, v159, v158
	v_cmp_ge_f32_e64 s[50:51], 0, v161
	v_add_u32_e32 v161, 1, v159
	s_nop 0
	v_cndmask_b32_e64 v160, v159, v160, s[50:51]
	v_fma_f32 v159, -v161, v159, v158
	v_cmp_lt_f32_e64 s[50:51], 0, v159
	s_nop 1
	v_cndmask_b32_e64 v159, v160, v161, s[50:51]
	v_mul_f32_e32 v160, 0x37800000, v159
	v_cndmask_b32_e32 v159, v159, v160, vcc
	v_cmp_class_f32_e32 vcc, v158, v200
	s_nop 1
	v_cndmask_b32_e32 v158, v159, v158, vcc
	v_div_scale_f32 v159, s[0:1], v158, v158, 1.0
	v_rcp_f32_e32 v160, v159
	s_nop 0
	v_fma_f32 v161, -v159, v160, 1.0
	v_fmac_f32_e32 v160, v161, v160
	v_div_scale_f32 v161, vcc, 1.0, v158, 1.0
	v_mul_f32_e32 v162, v161, v160
	v_fma_f32 v163, -v159, v162, v161
	v_fmac_f32_e32 v162, v163, v160
	v_fma_f32 v159, -v159, v162, v161
	v_div_fmas_f32 v159, v159, v160, v162
	v_div_fixup_f32 v158, v159, v158, 1.0
	v_pk_mul_f32 v[160:161], v[158:159], v[156:157] op_sel_hi:[0,1]
	v_pk_mul_f32 v[164:165], v[22:23], v[160:161]
	v_pk_mul_f32 v[160:161], v[158:159], v[154:155] op_sel_hi:[0,1]
	v_pk_mul_f32 v[162:163], v[24:25], v[160:161]
	v_pk_mul_f32 v[160:161], v[158:159], v[148:149] op_sel_hi:[0,1]
	v_pk_mul_f32 v[158:159], v[158:159], v[146:147] op_sel_hi:[0,1]
	v_pk_mul_f32 v[160:161], v[18:19], v[160:161]
	v_pk_mul_f32 v[158:159], v[20:21], v[158:159]
	ds_bpermute_b32 v172, v177, v164
	ds_bpermute_b32 v173, v177, v165
	ds_bpermute_b32 v170, v177, v162
	ds_bpermute_b32 v171, v177, v163
	ds_bpermute_b32 v168, v177, v160
	ds_bpermute_b32 v169, v177, v161
	ds_bpermute_b32 v166, v177, v158
	ds_bpermute_b32 v167, v177, v159
	s_and_saveexec_b64 s[0:1], s[46:47]
	s_xor_b64 s[0:1], exec, s[0:1]
	s_cbranch_execz .LBB0_338
	s_and_saveexec_b64 s[22:23], s[48:49]
	s_cbranch_execz .LBB0_337
	v_lshl_add_u64 v[130:131], s[4:5], 0, v[0:1]
	v_add_co_u32_e32 v130, vcc, 0x1326f000, v130
	s_nop 1
	v_addc_co_u32_e32 v131, vcc, 0, v131, vcc
	global_store_dwordx4 v[130:131], v[126:129], off offset:3840
